# census-guarded own-XCD-queue-only class loops (fallback to 8-queue stealing if an XCC id is unpopulated) + fox queue snapshot + barrier acquire-invalidate hoist
# speedup vs baseline: 1.0227x; 1.0070x over previous
; __device__ __forceinline__ unsigned xb_ld(unsigned* p)              { return __hip_atomic_load(p, __ATOMIC_RELAXED, __HIP_MEMORY_SCOPE_AGENT); }
; __device__ __forceinline__ unsigned xb_xcc_id() { return (unsigned)__builtin_amdgcn_s_getreg((3 << 11) | 20) & 0xFu; }
; #define WG_DRAW(cls, q) LAS int* slot = (LAS int*)(lds + MISC_OFF + 64); \
;         if (threadIdx.x == 0) *slot = (int)__hip_atomic_fetch_add(XQ_HEAD(cls, q), 1u, RLX_AGENT); \
;         __syncthreads(); const int it = *slot; __syncthreads();
; __device__ __forceinline__ void xcd_barrier_complete(unsigned* bar, unsigned x, unsigned& nloc, unsigned& nx) {
;     ...
;         for (unsigned j = 0; j < 16; ++j) { const unsigned c = xb_ld(&bar[XB_XCNT(j)]); sum += c; cnt += (c > 0u) ? 1u : 0u; mine = (j == x) ? c : mine; }
;         if (sum == G) break;
; template <int ATTM> __device__ __forceinline__ void attention_phase(int layer, int lane, int rep, LAS unsigned char* lds, int wave) {
;     ...
;     if ((ATTM & 2) && PK(2)) {
; #pragma unroll 1
;         for (int qq = 0; qq < 8; ++qq) { const int q = ((int)(xb_xcc_id() & 7u) + qq) & 7;
;             for (;;) { WG_DRAW(0, q); if (it >= 32) break;
.LBB0_544:
	s_load_dwordx2 s[12:13], s[0:1], 0x98
	v_and_b32_e32 v5, 7, v239
	v_lshlrev_b32_e32 v5, 8, v5
	v_add_u32_e32 v5, 0x4400, v5
	s_waitcnt lgkmcnt(0)
	global_load_dword v6, v5, s[12:13] sc1
	s_waitcnt vmcnt(0)
	v_cmp_ne_u32_e32 vcc, 0, v6
	s_nop 1
	s_and_b32 s100, vcc_lo, 0xff
	s_cmp_eq_u32 s100, 0xff
	s_cselect_b32 s100, 1, 8
	s_cmp_le_i32 s68, s4
	s_cselect_b64 s[2:3], -1, 0
	s_and_b64 s[4:5], s[2:3], s[14:15]
	s_mov_b64 s[2:3], -1
	s_and_b64 vcc, exec, s[4:5]
	s_cbranch_vccnz .LBB0_546
	v_readlane_b32 s2, v255, 20
	s_add_i32 s4, s2, 6
	s_mov_b64 s[2:3], 0

; __device__ __forceinline__ unsigned xb_xcc_id() { return (unsigned)__builtin_amdgcn_s_getreg((3 << 11) | 20) & 0xFu; }
; #define WG_DRAW(cls, q) LAS int* slot = (LAS int*)(lds + MISC_OFF + 64); \
;         if (threadIdx.x == 0) *slot = (int)__hip_atomic_fetch_add(XQ_HEAD(cls, q), 1u, RLX_AGENT); \
;         __syncthreads(); const int it = *slot; __syncthreads();
; template <int ATTM> __device__ __forceinline__ void attention_phase(int layer, int lane, int rep, LAS unsigned char* lds, int wave) {
;     ...
; #pragma unroll 1
;         for (int qq = 0; qq < 8; ++qq) { const int q = ((int)(xb_xcc_id() & 7u) + qq) & 7;
;             for (;;) { WG_DRAW(0, q); if (it >= 32) break;
.LBB0_548:
	s_add_i32 s6, s6, 1
	s_cmp_lg_u32 s6, s100
	s_cbranch_scc0 .LBB0_613

; __device__ __forceinline__ unsigned xb_xcc_id() { return (unsigned)__builtin_amdgcn_s_getreg((3 << 11) | 20) & 0xFu; }
; #define ARG_WS() ((unsigned char*)karg64(8 * 19))
; #define WG_DRAW(cls, q) LAS int* slot = (LAS int*)(lds + MISC_OFF + 64); \
;         if (threadIdx.x == 0) *slot = (int)__hip_atomic_fetch_add(XQ_HEAD(cls, q), 1u, RLX_AGENT); \
;         __syncthreads(); const int it = *slot; __syncthreads();
; template <int ATTM> __device__ __forceinline__ void attention_phase(int layer, int lane, int rep, LAS unsigned char* lds, int wave) {
;     ...
; #pragma unroll 1
;         for (int qq = 0; qq < 8; ++qq) { const int q = ((int)(xb_xcc_id() & 7u) + qq) & 7;
;             for (;;) { WG_DRAW(2, q); if (it >= 32) break; unsigned char* ws = ARG_WS();
.LBB0_669:
	s_add_i32 s59, s59, 1
	s_xor_b64 s[42:43], s[42:43], -1
	s_cmp_eq_u32 s59, s100
	s_cbranch_scc1 .LBB0_749

; __device__ __forceinline__ unsigned xb_xcc_id() { return (unsigned)__builtin_amdgcn_s_getreg((3 << 11) | 20) & 0xFu; }
; #define ARG_WS() ((unsigned char*)karg64(8 * 19))
; #define WV_DRAW(cls, q, n) int it = 0; if (__builtin_amdgcn_mbcnt_hi(~0u, __builtin_amdgcn_mbcnt_lo(~0u, 0u)) == 0u) it = (int)__hip_atomic_fetch_add(XQ_HEAD(cls, q), (unsigned)(n), RLX_AGENT); it = __builtin_amdgcn_readfirstlane(it);
; template <int ATTM> __device__ __forceinline__ void attention_phase(int layer, int lane, int rep, LAS unsigned char* lds, int wave) {
;     ...
; #pragma unroll 1
;         for (int qq = 0; qq < 8; ++qq) { const int q = ((int)(xb_xcc_id() & 7u) + qq) & 7;
;             for (;;) { WV_DRAW(3, q, 1); if (it >= 96) break; unsigned char* ws = ARG_WS();
.LBB0_750:
	s_add_i32 s7, s7, 1
	s_cmp_eq_u32 s7, s100
	s_cbranch_scc1 .LBB0_876

; __device__ __forceinline__ unsigned xb_xcc_id() { return (unsigned)__builtin_amdgcn_s_getreg((3 << 11) | 20) & 0xFu; }
; #define ARG_WS() ((unsigned char*)karg64(8 * 19))
; #define WV_DRAW(cls, q, n) int it = 0; if (__builtin_amdgcn_mbcnt_hi(~0u, __builtin_amdgcn_mbcnt_lo(~0u, 0u)) == 0u) it = (int)__hip_atomic_fetch_add(XQ_HEAD(cls, q), (unsigned)(n), RLX_AGENT); it = __builtin_amdgcn_readfirstlane(it);
; template <int ATTM> __device__ __forceinline__ void attention_phase(int layer, int lane, int rep, LAS unsigned char* lds, int wave) {
;     ...
; #pragma unroll 1
;         for (int qq = 0; qq < 8; ++qq) { const int q = ((int)(xb_xcc_id() & 7u) + qq) & 7;
;             for (;;) { WV_DRAW(4, q, 4); if (it >= I_LAYER / 8) break; unsigned char* ws = ARG_WS();
.LBB0_878:
	s_add_i32 s49, s49, 1
	s_add_i32 s50, s50, 1
	s_cmp_lg_u32 s49, s100
	s_cbranch_scc0 .LBB0_1428

; __device__ __forceinline__ unsigned xb_xcc_id() { return (unsigned)__builtin_amdgcn_s_getreg((3 << 11) | 20) & 0xFu; }
; #define ARG_WS() ((unsigned char*)karg64(8 * 19))
; template <int ATTM> __device__ __forceinline__ void attention_phase(int layer, int lane, int rep, LAS unsigned char* lds, int wave) {
;     ...
; #pragma unroll 1
;         for (int qq = 0; qq < 8; ++qq) { const int q = ((int)(xb_xcc_id() & 7u) + qq) & 7;
;             for (;;) { int it = 0; if (__builtin_amdgcn_mbcnt_hi(~0u, __builtin_amdgcn_mbcnt_lo(~0u, 0u)) == 0u) it = (int)__hip_atomic_fetch_add((gu32*)(ARG_WS() + WS_CTL) + CW_XQ + (((DEPTH * 5 + 4) * 8 + q) * 2 + rep) * 16, 4u, RLX_AGENT);
;                 it = __builtin_amdgcn_readfirstlane(it); if (it >= I_REST / 8) break; unsigned char* ws = ARG_WS();
.LBB0_1443:
	s_add_i32 s5, s5, 1
	s_add_i32 s26, s26, 1
	s_cmp_lg_u32 s5, s100
	s_cbranch_scc0 .LBB0_1429
